# grid barrier: non-leader workgroups issue the L1 invalidate before polling for the release, not after
# speedup vs baseline: 1.0158x; 1.0158x over previous
.LBB0_540:
	s_or_b64 exec, exec, s[8:9]
	v_cvt_f32_u32_e32 v4, v2
	s_waitcnt vmcnt(0)
	v_readfirstlane_b32 s8, v3
	v_sub_u32_e32 v3, 0, v2
	v_rcp_iflag_f32_e32 v4, v4
	v_add_u32_e32 v5, s8, v1
	v_mul_f32_e32 v4, 0x4f7ffffe, v4
	v_cvt_u32_f32_e32 v4, v4
	v_mul_lo_u32 v1, v3, v4
	v_mul_hi_u32 v1, v4, v1
	v_add_u32_e32 v1, v4, v1
	v_mul_hi_u32 v1, v5, v1
	v_mul_lo_u32 v3, v1, v2
	v_sub_u32_e32 v3, v5, v3
	v_add_u32_e32 v4, 1, v1
	v_cmp_ge_u32_e32 vcc, v3, v2
	s_nop 1
	v_cndmask_b32_e32 v1, v1, v4, vcc
	v_sub_u32_e32 v4, v3, v2
	v_cndmask_b32_e32 v3, v3, v4, vcc
	v_add_u32_e32 v4, 1, v1
	v_cmp_ge_u32_e32 vcc, v3, v2
	v_add_u32_e32 v3, 1, v5
	s_nop 0
	v_cndmask_b32_e32 v1, v1, v4, vcc
	v_mul_lo_u32 v4, v2, v1
	v_add_u32_e32 v2, v4, v2
	v_cmp_ne_u32_e32 vcc, v3, v2
	s_and_saveexec_b64 s[8:9], vcc
	s_xor_b64 s[8:9], exec, s[8:9]
	s_cbranch_execz .LBB0_554
	buffer_inv sc1
	v_readlane_b32 s10, v253, 11
	v_readlane_b32 s11, v253, 12
	s_waitcnt lgkmcnt(0)
	s_nop 3
	global_load_dword v0, v157, s[10:11] sc1
	s_waitcnt vmcnt(0)
	v_cmp_eq_u32_e32 vcc, v0, v1
	s_and_saveexec_b64 s[10:11], vcc
	s_cbranch_execz .LBB0_553
	s_mov_b32 s22, 1
	s_mov_b64 s[12:13], 0
	s_branch .LBB0_544

.LBB0_553:
	s_or_b64 exec, exec, s[10:11]
	s_waitcnt vmcnt(0)
	s_waitcnt vmcnt(0)
